# GEMM K-loops: LDS-DMA staging pieces rebalanced 2+6 -> 4+4 per K-tile (As[b][0] deferred one super-phase, waits 8->6)
# speedup vs baseline: 1.0072x; 1.0072x over previous
.LBB0_206:
	s_add_u32 s10, s22, 0xfffc0080
	s_addc_u32 s11, s23, -1
	s_add_i32 s12, 0, 0x10000
	s_cmp_eq_u32 vcc_hi, 12
	s_cselect_b32 s61, s9, s11
	s_cselect_b32 s60, s31, s10
	v_add_u32_e32 v152, s12, v157
	s_cselect_b32 s43, s41, vcc_lo
	s_cselect_b32 s42, s53, s55
	s_add_i32 s13, 0, 0x14000
	ds_read_b128 v[140:143], v152
	ds_read_b128 v[144:147], v152 offset:1024
	ds_read_b128 v[148:151], v152 offset:2048
	ds_read_b128 v[160:163], v152 offset:3072
	v_add_u32_e32 v152, s13, v157
	ds_read_b128 v[164:167], v152
	ds_read_b128 v[168:171], v152 offset:1024
	ds_read_b128 v[172:175], v152 offset:2048
	ds_read_b128 v[176:179], v152 offset:3072
	s_add_u32 s10, s22, 0xfffc0000
	s_addc_u32 s11, s23, -1
	v_lshl_add_u64 v[152:153], s[10:11], 0, v[136:137]
	s_mov_b32 m0, s83
	s_nop 0
	global_load_lds_dwordx4 v[152:153], off
	v_lshl_add_u64 v[152:153], s[10:11], 0, v[138:139]
	s_mov_b32 m0, s95
	s_nop 0
	global_load_lds_dwordx4 v[152:153], off
	v_lshl_add_u64 v[152:153], s[22:23], 0, v[136:137]
	s_add_i32 m0, s75, 0xc000
	ds_read_b128 v[180:183], v159
	ds_read_b128 v[184:187], v159 offset:1024
	ds_read_b128 v[188:191], v159 offset:2048
	ds_read_b128 v[206:209], v159 offset:3072
	ds_read_b128 v[210:213], v159 offset:4096
	ds_read_b128 v[214:217], v159 offset:5120
	ds_read_b128 v[218:221], v159 offset:6144
	ds_read_b128 v[222:225], v159 offset:7168
	global_load_lds_dwordx4 v[152:153], off
	v_lshl_add_u64 v[152:153], s[22:23], 0, v[138:139]
	s_add_i32 m0, s75, 0xe000
	s_nop 0
	global_load_lds_dwordx4 v[152:153], off
	s_waitcnt vmcnt(8)
	s_waitcnt lgkmcnt(0)
	s_barrier
	s_setprio 1
	s_waitcnt lgkmcnt(0)
	v_mfma_f32_16x16x32_bf16 v[124:127], v[140:143], v[180:183], v[124:127]
	v_mfma_f32_16x16x32_bf16 v[120:123], v[148:151], v[180:183], v[120:123]
	v_mfma_f32_16x16x32_bf16 v[108:111], v[140:143], v[188:191], v[108:111]
	v_mfma_f32_16x16x32_bf16 v[104:107], v[148:151], v[188:191], v[104:107]
	v_mfma_f32_16x16x32_bf16 v[92:95], v[140:143], v[210:213], v[92:95]
	v_mfma_f32_16x16x32_bf16 v[88:91], v[148:151], v[210:213], v[88:91]
	v_mfma_f32_16x16x32_bf16 v[76:79], v[140:143], v[218:221], v[76:79]
	v_mfma_f32_16x16x32_bf16 v[72:75], v[148:151], v[218:221], v[72:75]
	v_mfma_f32_16x16x32_bf16 v[124:127], v[144:147], v[184:187], v[124:127]
	v_mfma_f32_16x16x32_bf16 v[120:123], v[160:163], v[184:187], v[120:123]
	v_mfma_f32_16x16x32_bf16 v[108:111], v[144:147], v[206:209], v[108:111]
	v_mfma_f32_16x16x32_bf16 v[104:107], v[160:163], v[206:209], v[104:107]
	v_mfma_f32_16x16x32_bf16 v[92:95], v[144:147], v[214:217], v[92:95]
	v_mfma_f32_16x16x32_bf16 v[88:91], v[160:163], v[214:217], v[88:91]
	v_mfma_f32_16x16x32_bf16 v[76:79], v[144:147], v[222:225], v[76:79]
	v_mfma_f32_16x16x32_bf16 v[72:75], v[160:163], v[222:225], v[72:75]
	s_setprio 0
	s_setprio 1
	v_mfma_f32_16x16x32_bf16 v[116:119], v[164:167], v[180:183], v[116:119]
	v_mfma_f32_16x16x32_bf16 v[112:115], v[172:175], v[180:183], v[112:115]
	v_mfma_f32_16x16x32_bf16 v[100:103], v[164:167], v[188:191], v[100:103]
	v_mfma_f32_16x16x32_bf16 v[96:99], v[172:175], v[188:191], v[96:99]
	v_mfma_f32_16x16x32_bf16 v[84:87], v[164:167], v[210:213], v[84:87]
	v_mfma_f32_16x16x32_bf16 v[80:83], v[172:175], v[210:213], v[80:83]
	v_mfma_f32_16x16x32_bf16 v[68:71], v[164:167], v[218:221], v[68:71]
	v_mfma_f32_16x16x32_bf16 v[64:67], v[172:175], v[218:221], v[64:67]
	v_mfma_f32_16x16x32_bf16 v[116:119], v[168:171], v[184:187], v[116:119]
	v_mfma_f32_16x16x32_bf16 v[112:115], v[176:179], v[184:187], v[112:115]
	v_mfma_f32_16x16x32_bf16 v[100:103], v[168:171], v[206:209], v[100:103]
	v_mfma_f32_16x16x32_bf16 v[96:99], v[176:179], v[206:209], v[96:99]
	v_mfma_f32_16x16x32_bf16 v[84:87], v[168:171], v[214:217], v[84:87]
	v_mfma_f32_16x16x32_bf16 v[80:83], v[176:179], v[214:217], v[80:83]
	v_mfma_f32_16x16x32_bf16 v[68:71], v[168:171], v[222:225], v[68:71]
	v_mfma_f32_16x16x32_bf16 v[64:67], v[176:179], v[222:225], v[64:67]
	s_setprio 0
	s_barrier
	s_add_i32 s10, s12, s67
	v_lshl_add_u64 v[152:153], s[42:43], 0, v[192:193]
	s_mov_b32 m0, s10
	ds_read_b128 v[180:183], v159 offset:16384
	ds_read_b128 v[184:187], v159 offset:17408
	ds_read_b128 v[188:191], v159 offset:18432
	ds_read_b128 v[206:209], v159 offset:19456
	ds_read_b128 v[210:213], v159 offset:20480
	ds_read_b128 v[214:217], v159 offset:21504
	ds_read_b128 v[218:221], v159 offset:22528
	ds_read_b128 v[222:225], v159 offset:23552
	global_load_lds_dwordx4 v[152:153], off
	s_add_i32 m0, s10, 0x2000
	s_add_u32 s10, s42, 0x40000
	v_lshl_add_u64 v[226:227], s[42:43], 0, v[132:133]
	s_addc_u32 s11, s43, 0
	s_add_i32 s12, s13, s67
	global_load_lds_dwordx4 v[226:227], off
	v_lshl_add_u64 v[228:229], s[10:11], 0, v[192:193]
	s_mov_b32 m0, s12
	v_lshl_add_u64 v[230:231], s[60:61], 0, v[130:131]
	global_load_lds_dwordx4 v[228:229], off
	v_lshl_add_u64 v[228:229], s[10:11], 0, v[132:133]
	s_add_i32 m0, s12, 0x2000
	s_nop 0
	global_load_lds_dwordx4 v[228:229], off
	v_lshl_add_u64 v[228:229], s[60:61], 0, v[128:129]
	s_waitcnt vmcnt(6)
	s_waitcnt lgkmcnt(0)
	s_barrier
	s_setprio 1
	s_waitcnt lgkmcnt(0)
	v_mfma_f32_16x16x32_bf16 v[60:63], v[140:143], v[180:183], v[60:63]
	v_mfma_f32_16x16x32_bf16 v[56:59], v[148:151], v[180:183], v[56:59]
	v_mfma_f32_16x16x32_bf16 v[44:47], v[140:143], v[188:191], v[44:47]
	v_mfma_f32_16x16x32_bf16 v[40:43], v[148:151], v[188:191], v[40:43]
	v_mfma_f32_16x16x32_bf16 v[28:31], v[140:143], v[210:213], v[28:31]
	v_mfma_f32_16x16x32_bf16 v[24:27], v[148:151], v[210:213], v[24:27]
	v_mfma_f32_16x16x32_bf16 v[12:15], v[140:143], v[218:221], v[12:15]
	v_mfma_f32_16x16x32_bf16 v[8:11], v[148:151], v[218:221], v[8:11]
	v_mfma_f32_16x16x32_bf16 v[60:63], v[144:147], v[184:187], v[60:63]
	v_mfma_f32_16x16x32_bf16 v[56:59], v[160:163], v[184:187], v[56:59]
	v_mfma_f32_16x16x32_bf16 v[44:47], v[144:147], v[206:209], v[44:47]
	v_mfma_f32_16x16x32_bf16 v[40:43], v[160:163], v[206:209], v[40:43]
	v_mfma_f32_16x16x32_bf16 v[28:31], v[144:147], v[214:217], v[28:31]
	v_mfma_f32_16x16x32_bf16 v[24:27], v[160:163], v[214:217], v[24:27]
	v_mfma_f32_16x16x32_bf16 v[12:15], v[144:147], v[222:225], v[12:15]
	v_mfma_f32_16x16x32_bf16 v[8:11], v[160:163], v[222:225], v[8:11]
	s_setprio 0
	s_setprio 1
	v_mfma_f32_16x16x32_bf16 v[52:55], v[164:167], v[180:183], v[52:55]
	v_mfma_f32_16x16x32_bf16 v[48:51], v[172:175], v[180:183], v[48:51]
	v_mfma_f32_16x16x32_bf16 v[36:39], v[164:167], v[188:191], v[36:39]
	v_mfma_f32_16x16x32_bf16 v[32:35], v[172:175], v[188:191], v[32:35]
	v_mfma_f32_16x16x32_bf16 v[20:23], v[164:167], v[210:213], v[20:23]
	v_mfma_f32_16x16x32_bf16 v[16:19], v[172:175], v[210:213], v[16:19]
	v_mfma_f32_16x16x32_bf16 v[4:7], v[164:167], v[218:221], v[4:7]
	v_mfma_f32_16x16x32_bf16 v[0:3], v[172:175], v[218:221], v[0:3]
	v_mfma_f32_16x16x32_bf16 v[52:55], v[168:171], v[184:187], v[52:55]
	v_mfma_f32_16x16x32_bf16 v[48:51], v[176:179], v[184:187], v[48:51]
	v_mfma_f32_16x16x32_bf16 v[36:39], v[168:171], v[206:209], v[36:39]
	v_mfma_f32_16x16x32_bf16 v[32:35], v[176:179], v[206:209], v[32:35]
	v_mfma_f32_16x16x32_bf16 v[20:23], v[168:171], v[214:217], v[20:23]
	v_mfma_f32_16x16x32_bf16 v[16:19], v[176:179], v[214:217], v[16:19]
	v_mfma_f32_16x16x32_bf16 v[4:7], v[168:171], v[222:225], v[4:7]
	v_mfma_f32_16x16x32_bf16 v[0:3], v[176:179], v[222:225], v[0:3]
	s_setprio 0
	s_barrier
	s_add_i32 s12, 0, 0x18000
	s_add_i32 s13, 0, 0x1c000
	v_add_u32_e32 v160, s12, v157
	v_add_u32_e32 v176, s13, v157
	ds_read_b128 v[140:143], v160
	ds_read_b128 v[144:147], v160 offset:1024
	ds_read_b128 v[148:151], v160 offset:2048
	ds_read_b128 v[160:163], v160 offset:3072
	ds_read_b128 v[164:167], v176
	ds_read_b128 v[168:171], v176 offset:1024
	ds_read_b128 v[172:175], v176 offset:2048
	ds_read_b128 v[176:179], v176 offset:3072
	s_mov_b32 m0, s75
	s_nop 0
	global_load_lds_dwordx4 v[228:229], off
	s_mov_b32 m0, s78
	s_nop 0
	global_load_lds_dwordx4 v[230:231], off
	s_add_u32 s10, s60, 0x40000
	s_addc_u32 s11, s61, 0
	s_mov_b32 m0, s79
	v_lshl_add_u64 v[232:233], s[10:11], 0, v[128:129]
	ds_read_b128 v[180:183], v159 offset:32768
	ds_read_b128 v[184:187], v159 offset:33792
	ds_read_b128 v[188:191], v159 offset:34816
	ds_read_b128 v[206:209], v159 offset:35840
	ds_read_b128 v[210:213], v159 offset:36864
	ds_read_b128 v[214:217], v159 offset:37888
	ds_read_b128 v[218:221], v159 offset:38912
	ds_read_b128 v[222:225], v159 offset:39936
	global_load_lds_dwordx4 v[232:233], off
	v_lshl_add_u64 v[232:233], s[10:11], 0, v[130:131]
	s_mov_b32 m0, s82
	s_nop 0
	global_load_lds_dwordx4 v[232:233], off
	s_waitcnt vmcnt(8)
	s_waitcnt lgkmcnt(0)
	s_barrier
	s_setprio 1
	s_waitcnt lgkmcnt(0)
	v_mfma_f32_16x16x32_bf16 v[124:127], v[140:143], v[180:183], v[124:127]
	v_mfma_f32_16x16x32_bf16 v[120:123], v[148:151], v[180:183], v[120:123]
	v_mfma_f32_16x16x32_bf16 v[108:111], v[140:143], v[188:191], v[108:111]
	v_mfma_f32_16x16x32_bf16 v[104:107], v[148:151], v[188:191], v[104:107]
	v_mfma_f32_16x16x32_bf16 v[92:95], v[140:143], v[210:213], v[92:95]
	v_mfma_f32_16x16x32_bf16 v[88:91], v[148:151], v[210:213], v[88:91]
	v_mfma_f32_16x16x32_bf16 v[76:79], v[140:143], v[218:221], v[76:79]
	v_mfma_f32_16x16x32_bf16 v[72:75], v[148:151], v[218:221], v[72:75]
	v_mfma_f32_16x16x32_bf16 v[124:127], v[144:147], v[184:187], v[124:127]
	v_mfma_f32_16x16x32_bf16 v[120:123], v[160:163], v[184:187], v[120:123]
	v_mfma_f32_16x16x32_bf16 v[108:111], v[144:147], v[206:209], v[108:111]
	v_mfma_f32_16x16x32_bf16 v[104:107], v[160:163], v[206:209], v[104:107]
	v_mfma_f32_16x16x32_bf16 v[92:95], v[144:147], v[214:217], v[92:95]
	v_mfma_f32_16x16x32_bf16 v[88:91], v[160:163], v[214:217], v[88:91]
	v_mfma_f32_16x16x32_bf16 v[76:79], v[144:147], v[222:225], v[76:79]
	v_mfma_f32_16x16x32_bf16 v[72:75], v[160:163], v[222:225], v[72:75]
	s_setprio 0
	s_setprio 1
	v_mfma_f32_16x16x32_bf16 v[116:119], v[164:167], v[180:183], v[116:119]
	v_mfma_f32_16x16x32_bf16 v[112:115], v[172:175], v[180:183], v[112:115]
	v_mfma_f32_16x16x32_bf16 v[100:103], v[164:167], v[188:191], v[100:103]
	v_mfma_f32_16x16x32_bf16 v[96:99], v[172:175], v[188:191], v[96:99]
	v_mfma_f32_16x16x32_bf16 v[84:87], v[164:167], v[210:213], v[84:87]
	v_mfma_f32_16x16x32_bf16 v[80:83], v[172:175], v[210:213], v[80:83]
	v_mfma_f32_16x16x32_bf16 v[68:71], v[164:167], v[218:221], v[68:71]
	v_mfma_f32_16x16x32_bf16 v[64:67], v[172:175], v[218:221], v[64:67]
	v_mfma_f32_16x16x32_bf16 v[116:119], v[168:171], v[184:187], v[116:119]
	v_mfma_f32_16x16x32_bf16 v[112:115], v[176:179], v[184:187], v[112:115]
	v_mfma_f32_16x16x32_bf16 v[100:103], v[168:171], v[206:209], v[100:103]
	v_mfma_f32_16x16x32_bf16 v[96:99], v[176:179], v[206:209], v[96:99]
	v_mfma_f32_16x16x32_bf16 v[84:87], v[168:171], v[214:217], v[84:87]
	v_mfma_f32_16x16x32_bf16 v[80:83], v[176:179], v[214:217], v[80:83]
	v_mfma_f32_16x16x32_bf16 v[68:71], v[168:171], v[222:225], v[68:71]
	v_mfma_f32_16x16x32_bf16 v[64:67], v[176:179], v[222:225], v[64:67]
	s_setprio 0
	s_barrier
	s_add_i32 s10, s12, s67
	v_lshl_add_u64 v[152:153], v[152:153], 0, s[28:29]
	s_mov_b32 m0, s10
	ds_read_b128 v[180:183], v159 offset:49152
	ds_read_b128 v[184:187], v159 offset:50176
	ds_read_b128 v[188:191], v159 offset:51200
	ds_read_b128 v[206:209], v159 offset:52224
	ds_read_b128 v[210:213], v159 offset:53248
	ds_read_b128 v[214:217], v159 offset:54272
	ds_read_b128 v[218:221], v159 offset:55296
	ds_read_b128 v[222:225], v159 offset:56320
	global_load_lds_dwordx4 v[152:153], off
	s_add_i32 m0, s10, 0x2000
	s_add_u32 s10, s42, 0x40080
	v_lshl_add_u64 v[152:153], v[226:227], 0, s[28:29]
	s_addc_u32 s11, s43, 0
	s_add_i32 s12, s13, s67
	global_load_lds_dwordx4 v[152:153], off
	v_lshl_add_u64 v[152:153], s[10:11], 0, v[192:193]
	s_mov_b32 m0, s12
	s_nop 0
	global_load_lds_dwordx4 v[152:153], off
	v_lshl_add_u64 v[152:153], s[10:11], 0, v[132:133]
	s_add_i32 m0, s12, 0x2000
	s_nop 0
	global_load_lds_dwordx4 v[152:153], off
	s_waitcnt vmcnt(6)
	s_waitcnt lgkmcnt(0)
	s_barrier
	s_setprio 1
	s_waitcnt lgkmcnt(0)
	v_mfma_f32_16x16x32_bf16 v[60:63], v[140:143], v[180:183], v[60:63]
	v_mfma_f32_16x16x32_bf16 v[56:59], v[148:151], v[180:183], v[56:59]
	v_mfma_f32_16x16x32_bf16 v[44:47], v[140:143], v[188:191], v[44:47]
	v_mfma_f32_16x16x32_bf16 v[40:43], v[148:151], v[188:191], v[40:43]
	v_mfma_f32_16x16x32_bf16 v[28:31], v[140:143], v[210:213], v[28:31]
	v_mfma_f32_16x16x32_bf16 v[24:27], v[148:151], v[210:213], v[24:27]
	v_mfma_f32_16x16x32_bf16 v[12:15], v[140:143], v[218:221], v[12:15]
	v_mfma_f32_16x16x32_bf16 v[8:11], v[148:151], v[218:221], v[8:11]
	v_mfma_f32_16x16x32_bf16 v[60:63], v[144:147], v[184:187], v[60:63]
	v_mfma_f32_16x16x32_bf16 v[56:59], v[160:163], v[184:187], v[56:59]
	v_mfma_f32_16x16x32_bf16 v[44:47], v[144:147], v[206:209], v[44:47]
	v_mfma_f32_16x16x32_bf16 v[40:43], v[160:163], v[206:209], v[40:43]
	v_mfma_f32_16x16x32_bf16 v[28:31], v[144:147], v[214:217], v[28:31]
	v_mfma_f32_16x16x32_bf16 v[24:27], v[160:163], v[214:217], v[24:27]
	v_mfma_f32_16x16x32_bf16 v[12:15], v[144:147], v[222:225], v[12:15]
	v_mfma_f32_16x16x32_bf16 v[8:11], v[160:163], v[222:225], v[8:11]
	s_setprio 0
	s_setprio 1
	v_mfma_f32_16x16x32_bf16 v[52:55], v[164:167], v[180:183], v[52:55]
	v_mfma_f32_16x16x32_bf16 v[48:51], v[172:175], v[180:183], v[48:51]
	v_mfma_f32_16x16x32_bf16 v[36:39], v[164:167], v[188:191], v[36:39]
	v_mfma_f32_16x16x32_bf16 v[32:35], v[172:175], v[188:191], v[32:35]
	v_mfma_f32_16x16x32_bf16 v[20:23], v[164:167], v[210:213], v[20:23]
	v_mfma_f32_16x16x32_bf16 v[16:19], v[172:175], v[210:213], v[16:19]
	v_mfma_f32_16x16x32_bf16 v[4:7], v[164:167], v[218:221], v[4:7]
	v_mfma_f32_16x16x32_bf16 v[0:3], v[172:175], v[218:221], v[0:3]
	v_mfma_f32_16x16x32_bf16 v[52:55], v[168:171], v[184:187], v[52:55]
	v_mfma_f32_16x16x32_bf16 v[48:51], v[176:179], v[184:187], v[48:51]
	v_mfma_f32_16x16x32_bf16 v[36:39], v[168:171], v[206:209], v[36:39]
	v_mfma_f32_16x16x32_bf16 v[32:35], v[176:179], v[206:209], v[32:35]
	v_mfma_f32_16x16x32_bf16 v[20:23], v[168:171], v[214:217], v[20:23]
	v_mfma_f32_16x16x32_bf16 v[16:19], v[176:179], v[214:217], v[16:19]
	v_mfma_f32_16x16x32_bf16 v[4:7], v[168:171], v[222:225], v[4:7]
	v_mfma_f32_16x16x32_bf16 v[0:3], v[176:179], v[222:225], v[0:3]
	s_setprio 0
	s_barrier
	s_add_i32 vcc_hi, vcc_hi, 2
	s_add_u32 s22, s22, 0x100
	s_addc_u32 s23, s23, 0
	s_add_u32 s55, s55, 0x100
	s_addc_u32 vcc_lo, vcc_lo, 0
	s_cmp_gt_u32 vcc_hi, 13
	s_cbranch_scc0 .LBB0_206
	s_and_b64 vcc, exec, s[48:49]
	s_cbranch_vccz .LBB0_209
	s_barrier

.LBB0_1039:
	s_add_u32 s10, s60, 0xfffc0080
	s_addc_u32 s11, s61, -1
	s_add_i32 s12, 0, 0x10000
	s_cmp_eq_u32 s96, 12
	s_cselect_b32 s65, s51, s11
	s_cselect_b32 s64, s57, s10
	v_add_u32_e32 v142, s12, v147
	s_cselect_b32 s63, s49, s95
	s_cselect_b32 s62, s82, s83
	s_add_i32 s13, 0, 0x14000
	ds_read_b128 v[138:141], v142
	ds_read_b128 v[150:153], v142 offset:1024
	ds_read_b128 v[154:157], v142 offset:2048
	ds_read_b128 v[158:161], v142 offset:3072
	v_add_u32_e32 v142, s13, v147
	ds_read_b128 v[162:165], v142
	ds_read_b128 v[166:169], v142 offset:1024
	ds_read_b128 v[170:173], v142 offset:2048
	ds_read_b128 v[174:177], v142 offset:3072
	s_add_u32 s10, s60, 0xfffc0000
	s_addc_u32 s11, s61, -1
	v_lshl_add_u64 v[142:143], s[10:11], 0, v[134:135]
	s_mov_b32 m0, s66
	s_nop 0
	global_load_lds_dwordx4 v[142:143], off
	v_lshl_add_u64 v[142:143], s[10:11], 0, v[136:137]
	s_mov_b32 m0, s67
	s_nop 0
	global_load_lds_dwordx4 v[142:143], off
	v_lshl_add_u64 v[142:143], s[60:61], 0, v[134:135]
	s_add_i32 m0, s8, 0xc000
	ds_read_b128 v[178:181], v149
	ds_read_b128 v[182:185], v149 offset:1024
	ds_read_b128 v[186:189], v149 offset:2048
	ds_read_b128 v[206:209], v149 offset:3072
	ds_read_b128 v[210:213], v149 offset:4096
	ds_read_b128 v[214:217], v149 offset:5120
	ds_read_b128 v[218:221], v149 offset:6144
	ds_read_b128 v[222:225], v149 offset:7168
	global_load_lds_dwordx4 v[142:143], off
	v_lshl_add_u64 v[142:143], s[60:61], 0, v[136:137]
	s_add_i32 m0, s8, 0xe000
	s_nop 0
	global_load_lds_dwordx4 v[142:143], off
	s_waitcnt vmcnt(8)
	s_waitcnt lgkmcnt(0)
	s_barrier
	s_setprio 1
	s_waitcnt lgkmcnt(0)
	v_mfma_f32_16x16x32_bf16 v[124:127], v[138:141], v[178:181], v[124:127]
	v_mfma_f32_16x16x32_bf16 v[120:123], v[154:157], v[178:181], v[120:123]
	v_mfma_f32_16x16x32_bf16 v[108:111], v[138:141], v[186:189], v[108:111]
	v_mfma_f32_16x16x32_bf16 v[104:107], v[154:157], v[186:189], v[104:107]
	v_mfma_f32_16x16x32_bf16 v[92:95], v[138:141], v[210:213], v[92:95]
	v_mfma_f32_16x16x32_bf16 v[88:91], v[154:157], v[210:213], v[88:91]
	v_mfma_f32_16x16x32_bf16 v[76:79], v[138:141], v[218:221], v[76:79]
	v_mfma_f32_16x16x32_bf16 v[72:75], v[154:157], v[218:221], v[72:75]
	v_mfma_f32_16x16x32_bf16 v[124:127], v[150:153], v[182:185], v[124:127]
	v_mfma_f32_16x16x32_bf16 v[120:123], v[158:161], v[182:185], v[120:123]
	v_mfma_f32_16x16x32_bf16 v[108:111], v[150:153], v[206:209], v[108:111]
	v_mfma_f32_16x16x32_bf16 v[104:107], v[158:161], v[206:209], v[104:107]
	v_mfma_f32_16x16x32_bf16 v[92:95], v[150:153], v[214:217], v[92:95]
	v_mfma_f32_16x16x32_bf16 v[88:91], v[158:161], v[214:217], v[88:91]
	v_mfma_f32_16x16x32_bf16 v[76:79], v[150:153], v[222:225], v[76:79]
	v_mfma_f32_16x16x32_bf16 v[72:75], v[158:161], v[222:225], v[72:75]
	s_setprio 0
	s_setprio 1
	v_mfma_f32_16x16x32_bf16 v[116:119], v[162:165], v[178:181], v[116:119]
	v_mfma_f32_16x16x32_bf16 v[112:115], v[170:173], v[178:181], v[112:115]
	v_mfma_f32_16x16x32_bf16 v[100:103], v[162:165], v[186:189], v[100:103]
	v_mfma_f32_16x16x32_bf16 v[96:99], v[170:173], v[186:189], v[96:99]
	v_mfma_f32_16x16x32_bf16 v[84:87], v[162:165], v[210:213], v[84:87]
	v_mfma_f32_16x16x32_bf16 v[80:83], v[170:173], v[210:213], v[80:83]
	v_mfma_f32_16x16x32_bf16 v[68:71], v[162:165], v[218:221], v[68:71]
	v_mfma_f32_16x16x32_bf16 v[64:67], v[170:173], v[218:221], v[64:67]
	v_mfma_f32_16x16x32_bf16 v[116:119], v[166:169], v[182:185], v[116:119]
	v_mfma_f32_16x16x32_bf16 v[112:115], v[174:177], v[182:185], v[112:115]
	v_mfma_f32_16x16x32_bf16 v[100:103], v[166:169], v[206:209], v[100:103]
	v_mfma_f32_16x16x32_bf16 v[96:99], v[174:177], v[206:209], v[96:99]
	v_mfma_f32_16x16x32_bf16 v[84:87], v[166:169], v[214:217], v[84:87]
	v_mfma_f32_16x16x32_bf16 v[80:83], v[174:177], v[214:217], v[80:83]
	v_mfma_f32_16x16x32_bf16 v[68:71], v[166:169], v[222:225], v[68:71]
	v_mfma_f32_16x16x32_bf16 v[64:67], v[174:177], v[222:225], v[64:67]
	s_setprio 0
	s_barrier
	s_add_i32 s10, s12, s7
	v_lshl_add_u64 v[142:143], s[62:63], 0, v[192:193]
	s_mov_b32 m0, s10
	ds_read_b128 v[178:181], v149 offset:16384
	ds_read_b128 v[182:185], v149 offset:17408
	ds_read_b128 v[186:189], v149 offset:18432
	ds_read_b128 v[206:209], v149 offset:19456
	ds_read_b128 v[210:213], v149 offset:20480
	ds_read_b128 v[214:217], v149 offset:21504
	ds_read_b128 v[218:221], v149 offset:22528
	ds_read_b128 v[222:225], v149 offset:23552
	global_load_lds_dwordx4 v[142:143], off
	s_add_i32 m0, s10, 0x2000
	s_add_u32 s10, s62, 0x40000
	v_lshl_add_u64 v[190:191], s[62:63], 0, v[132:133]
	s_addc_u32 s11, s63, 0
	s_add_i32 s12, s13, s7
	global_load_lds_dwordx4 v[190:191], off
	v_lshl_add_u64 v[226:227], s[10:11], 0, v[192:193]
	s_mov_b32 m0, s12
	v_lshl_add_u64 v[228:229], s[64:65], 0, v[130:131]
	global_load_lds_dwordx4 v[226:227], off
	v_lshl_add_u64 v[226:227], s[10:11], 0, v[132:133]
	s_add_i32 m0, s12, 0x2000
	s_nop 0
	global_load_lds_dwordx4 v[226:227], off
	v_lshl_add_u64 v[226:227], s[64:65], 0, v[128:129]
	s_waitcnt vmcnt(6)
	s_waitcnt lgkmcnt(0)
	s_barrier
	s_setprio 1
	s_waitcnt lgkmcnt(0)
	v_mfma_f32_16x16x32_bf16 v[60:63], v[138:141], v[178:181], v[60:63]
	v_mfma_f32_16x16x32_bf16 v[56:59], v[154:157], v[178:181], v[56:59]
	v_mfma_f32_16x16x32_bf16 v[44:47], v[138:141], v[186:189], v[44:47]
	v_mfma_f32_16x16x32_bf16 v[40:43], v[154:157], v[186:189], v[40:43]
	v_mfma_f32_16x16x32_bf16 v[28:31], v[138:141], v[210:213], v[28:31]
	v_mfma_f32_16x16x32_bf16 v[24:27], v[154:157], v[210:213], v[24:27]
	v_mfma_f32_16x16x32_bf16 v[12:15], v[138:141], v[218:221], v[12:15]
	v_mfma_f32_16x16x32_bf16 v[8:11], v[154:157], v[218:221], v[8:11]
	v_mfma_f32_16x16x32_bf16 v[60:63], v[150:153], v[182:185], v[60:63]
	v_mfma_f32_16x16x32_bf16 v[56:59], v[158:161], v[182:185], v[56:59]
	v_mfma_f32_16x16x32_bf16 v[44:47], v[150:153], v[206:209], v[44:47]
	v_mfma_f32_16x16x32_bf16 v[40:43], v[158:161], v[206:209], v[40:43]
	v_mfma_f32_16x16x32_bf16 v[28:31], v[150:153], v[214:217], v[28:31]
	v_mfma_f32_16x16x32_bf16 v[24:27], v[158:161], v[214:217], v[24:27]
	v_mfma_f32_16x16x32_bf16 v[12:15], v[150:153], v[222:225], v[12:15]
	v_mfma_f32_16x16x32_bf16 v[8:11], v[158:161], v[222:225], v[8:11]
	s_setprio 0
	s_setprio 1
	v_mfma_f32_16x16x32_bf16 v[52:55], v[162:165], v[178:181], v[52:55]
	v_mfma_f32_16x16x32_bf16 v[48:51], v[170:173], v[178:181], v[48:51]
	v_mfma_f32_16x16x32_bf16 v[36:39], v[162:165], v[186:189], v[36:39]
	v_mfma_f32_16x16x32_bf16 v[32:35], v[170:173], v[186:189], v[32:35]
	v_mfma_f32_16x16x32_bf16 v[20:23], v[162:165], v[210:213], v[20:23]
	v_mfma_f32_16x16x32_bf16 v[16:19], v[170:173], v[210:213], v[16:19]
	v_mfma_f32_16x16x32_bf16 v[4:7], v[162:165], v[218:221], v[4:7]
	v_mfma_f32_16x16x32_bf16 v[0:3], v[170:173], v[218:221], v[0:3]
	v_mfma_f32_16x16x32_bf16 v[52:55], v[166:169], v[182:185], v[52:55]
	v_mfma_f32_16x16x32_bf16 v[48:51], v[174:177], v[182:185], v[48:51]
	v_mfma_f32_16x16x32_bf16 v[36:39], v[166:169], v[206:209], v[36:39]
	v_mfma_f32_16x16x32_bf16 v[32:35], v[174:177], v[206:209], v[32:35]
	v_mfma_f32_16x16x32_bf16 v[20:23], v[166:169], v[214:217], v[20:23]
	v_mfma_f32_16x16x32_bf16 v[16:19], v[174:177], v[214:217], v[16:19]
	v_mfma_f32_16x16x32_bf16 v[4:7], v[166:169], v[222:225], v[4:7]
	v_mfma_f32_16x16x32_bf16 v[0:3], v[174:177], v[222:225], v[0:3]
	s_setprio 0
	s_barrier
	s_add_i32 s12, 0, 0x18000
	s_add_i32 s13, 0, 0x1c000
	v_add_u32_e32 v158, s12, v147
	v_add_u32_e32 v174, s13, v147
	ds_read_b128 v[138:141], v158
	ds_read_b128 v[150:153], v158 offset:1024
	ds_read_b128 v[154:157], v158 offset:2048
	ds_read_b128 v[158:161], v158 offset:3072
	ds_read_b128 v[162:165], v174
	ds_read_b128 v[166:169], v174 offset:1024
	ds_read_b128 v[170:173], v174 offset:2048
	ds_read_b128 v[174:177], v174 offset:3072
	s_mov_b32 m0, s8
	s_nop 0
	global_load_lds_dwordx4 v[226:227], off
	s_mov_b32 m0, s9
	s_nop 0
	global_load_lds_dwordx4 v[228:229], off
	s_add_u32 s10, s64, 0x40000
	s_addc_u32 s11, s65, 0
	s_mov_b32 m0, s26
	v_lshl_add_u64 v[230:231], s[10:11], 0, v[128:129]
	ds_read_b128 v[178:181], v149 offset:32768
	ds_read_b128 v[182:185], v149 offset:33792
	ds_read_b128 v[186:189], v149 offset:34816
	ds_read_b128 v[206:209], v149 offset:35840
	ds_read_b128 v[210:213], v149 offset:36864
	ds_read_b128 v[214:217], v149 offset:37888
	ds_read_b128 v[218:221], v149 offset:38912
	ds_read_b128 v[222:225], v149 offset:39936
	global_load_lds_dwordx4 v[230:231], off
	v_lshl_add_u64 v[230:231], s[10:11], 0, v[130:131]
	s_mov_b32 m0, s59
	s_nop 0
	global_load_lds_dwordx4 v[230:231], off
	s_waitcnt vmcnt(8)
	s_waitcnt lgkmcnt(0)
	s_barrier
	s_setprio 1
	s_waitcnt lgkmcnt(0)
	v_mfma_f32_16x16x32_bf16 v[124:127], v[138:141], v[178:181], v[124:127]
	v_mfma_f32_16x16x32_bf16 v[120:123], v[154:157], v[178:181], v[120:123]
	v_mfma_f32_16x16x32_bf16 v[108:111], v[138:141], v[186:189], v[108:111]
	v_mfma_f32_16x16x32_bf16 v[104:107], v[154:157], v[186:189], v[104:107]
	v_mfma_f32_16x16x32_bf16 v[92:95], v[138:141], v[210:213], v[92:95]
	v_mfma_f32_16x16x32_bf16 v[88:91], v[154:157], v[210:213], v[88:91]
	v_mfma_f32_16x16x32_bf16 v[76:79], v[138:141], v[218:221], v[76:79]
	v_mfma_f32_16x16x32_bf16 v[72:75], v[154:157], v[218:221], v[72:75]
	v_mfma_f32_16x16x32_bf16 v[124:127], v[150:153], v[182:185], v[124:127]
	v_mfma_f32_16x16x32_bf16 v[120:123], v[158:161], v[182:185], v[120:123]
	v_mfma_f32_16x16x32_bf16 v[108:111], v[150:153], v[206:209], v[108:111]
	v_mfma_f32_16x16x32_bf16 v[104:107], v[158:161], v[206:209], v[104:107]
	v_mfma_f32_16x16x32_bf16 v[92:95], v[150:153], v[214:217], v[92:95]
	v_mfma_f32_16x16x32_bf16 v[88:91], v[158:161], v[214:217], v[88:91]
	v_mfma_f32_16x16x32_bf16 v[76:79], v[150:153], v[222:225], v[76:79]
	v_mfma_f32_16x16x32_bf16 v[72:75], v[158:161], v[222:225], v[72:75]
	s_setprio 0
	s_setprio 1
	v_mfma_f32_16x16x32_bf16 v[116:119], v[162:165], v[178:181], v[116:119]
	v_mfma_f32_16x16x32_bf16 v[112:115], v[170:173], v[178:181], v[112:115]
	v_mfma_f32_16x16x32_bf16 v[100:103], v[162:165], v[186:189], v[100:103]
	v_mfma_f32_16x16x32_bf16 v[96:99], v[170:173], v[186:189], v[96:99]
	v_mfma_f32_16x16x32_bf16 v[84:87], v[162:165], v[210:213], v[84:87]
	v_mfma_f32_16x16x32_bf16 v[80:83], v[170:173], v[210:213], v[80:83]
	v_mfma_f32_16x16x32_bf16 v[68:71], v[162:165], v[218:221], v[68:71]
	v_mfma_f32_16x16x32_bf16 v[64:67], v[170:173], v[218:221], v[64:67]
	v_mfma_f32_16x16x32_bf16 v[116:119], v[166:169], v[182:185], v[116:119]
	v_mfma_f32_16x16x32_bf16 v[112:115], v[174:177], v[182:185], v[112:115]
	v_mfma_f32_16x16x32_bf16 v[100:103], v[166:169], v[206:209], v[100:103]
	v_mfma_f32_16x16x32_bf16 v[96:99], v[174:177], v[206:209], v[96:99]
	v_mfma_f32_16x16x32_bf16 v[84:87], v[166:169], v[214:217], v[84:87]
	v_mfma_f32_16x16x32_bf16 v[80:83], v[174:177], v[214:217], v[80:83]
	v_mfma_f32_16x16x32_bf16 v[68:71], v[166:169], v[222:225], v[68:71]
	v_mfma_f32_16x16x32_bf16 v[64:67], v[174:177], v[222:225], v[64:67]
	s_setprio 0
	s_barrier
	s_add_i32 s10, s12, s7
	v_lshl_add_u64 v[142:143], v[142:143], 0, s[28:29]
	s_mov_b32 m0, s10
	ds_read_b128 v[178:181], v149 offset:49152
	ds_read_b128 v[182:185], v149 offset:50176
	ds_read_b128 v[186:189], v149 offset:51200
	ds_read_b128 v[206:209], v149 offset:52224
	ds_read_b128 v[210:213], v149 offset:53248
	ds_read_b128 v[214:217], v149 offset:54272
	ds_read_b128 v[218:221], v149 offset:55296
	ds_read_b128 v[222:225], v149 offset:56320
	global_load_lds_dwordx4 v[142:143], off
	s_add_i32 m0, s10, 0x2000
	s_add_u32 s10, s62, 0x40080
	v_lshl_add_u64 v[142:143], v[190:191], 0, s[28:29]
	s_addc_u32 s11, s63, 0
	s_add_i32 s12, s13, s7
	global_load_lds_dwordx4 v[142:143], off
	v_lshl_add_u64 v[142:143], s[10:11], 0, v[192:193]
	s_mov_b32 m0, s12
	s_nop 0
	global_load_lds_dwordx4 v[142:143], off
	v_lshl_add_u64 v[142:143], s[10:11], 0, v[132:133]
	s_add_i32 m0, s12, 0x2000
	s_nop 0
	global_load_lds_dwordx4 v[142:143], off
	s_waitcnt vmcnt(6)
	s_waitcnt lgkmcnt(0)
	s_barrier
	s_setprio 1
	s_waitcnt lgkmcnt(0)
	v_mfma_f32_16x16x32_bf16 v[60:63], v[138:141], v[178:181], v[60:63]
	v_mfma_f32_16x16x32_bf16 v[56:59], v[154:157], v[178:181], v[56:59]
	v_mfma_f32_16x16x32_bf16 v[44:47], v[138:141], v[186:189], v[44:47]
	v_mfma_f32_16x16x32_bf16 v[40:43], v[154:157], v[186:189], v[40:43]
	v_mfma_f32_16x16x32_bf16 v[28:31], v[138:141], v[210:213], v[28:31]
	v_mfma_f32_16x16x32_bf16 v[24:27], v[154:157], v[210:213], v[24:27]
	v_mfma_f32_16x16x32_bf16 v[12:15], v[138:141], v[218:221], v[12:15]
	v_mfma_f32_16x16x32_bf16 v[8:11], v[154:157], v[218:221], v[8:11]
	v_mfma_f32_16x16x32_bf16 v[60:63], v[150:153], v[182:185], v[60:63]
	v_mfma_f32_16x16x32_bf16 v[56:59], v[158:161], v[182:185], v[56:59]
	v_mfma_f32_16x16x32_bf16 v[44:47], v[150:153], v[206:209], v[44:47]
	v_mfma_f32_16x16x32_bf16 v[40:43], v[158:161], v[206:209], v[40:43]
	v_mfma_f32_16x16x32_bf16 v[28:31], v[150:153], v[214:217], v[28:31]
	v_mfma_f32_16x16x32_bf16 v[24:27], v[158:161], v[214:217], v[24:27]
	v_mfma_f32_16x16x32_bf16 v[12:15], v[150:153], v[222:225], v[12:15]
	v_mfma_f32_16x16x32_bf16 v[8:11], v[158:161], v[222:225], v[8:11]
	s_setprio 0
	s_setprio 1
	v_mfma_f32_16x16x32_bf16 v[52:55], v[162:165], v[178:181], v[52:55]
	v_mfma_f32_16x16x32_bf16 v[48:51], v[170:173], v[178:181], v[48:51]
	v_mfma_f32_16x16x32_bf16 v[36:39], v[162:165], v[186:189], v[36:39]
	v_mfma_f32_16x16x32_bf16 v[32:35], v[170:173], v[186:189], v[32:35]
	v_mfma_f32_16x16x32_bf16 v[20:23], v[162:165], v[210:213], v[20:23]
	v_mfma_f32_16x16x32_bf16 v[16:19], v[170:173], v[210:213], v[16:19]
	v_mfma_f32_16x16x32_bf16 v[4:7], v[162:165], v[218:221], v[4:7]
	v_mfma_f32_16x16x32_bf16 v[0:3], v[170:173], v[218:221], v[0:3]
	v_mfma_f32_16x16x32_bf16 v[52:55], v[166:169], v[182:185], v[52:55]
	v_mfma_f32_16x16x32_bf16 v[48:51], v[174:177], v[182:185], v[48:51]
	v_mfma_f32_16x16x32_bf16 v[36:39], v[166:169], v[206:209], v[36:39]
	v_mfma_f32_16x16x32_bf16 v[32:35], v[174:177], v[206:209], v[32:35]
	v_mfma_f32_16x16x32_bf16 v[20:23], v[166:169], v[214:217], v[20:23]
	v_mfma_f32_16x16x32_bf16 v[16:19], v[174:177], v[214:217], v[16:19]
	v_mfma_f32_16x16x32_bf16 v[4:7], v[166:169], v[222:225], v[4:7]
	v_mfma_f32_16x16x32_bf16 v[0:3], v[174:177], v[222:225], v[0:3]
	s_setprio 0
	s_barrier
	s_add_i32 s96, s96, 2
	s_add_u32 s60, s60, 0x100
	s_addc_u32 s61, s61, 0
	s_add_u32 s83, s83, 0x100
	s_addc_u32 s95, s95, 0
	s_cmp_gt_u32 s96, 13
	s_cbranch_scc0 .LBB0_1039
	s_and_b64 vcc, exec, s[46:47]
	s_cbranch_vccz .LBB0_1042
	s_barrier

.LBB0_1144:
	s_add_u32 s10, s30, 0xfffc0080
	s_addc_u32 s11, s31, -1
	s_add_i32 s12, 0, 0x10000
	s_cmp_eq_u32 s47, 12
	s_cselect_b32 s55, s5, s11
	s_cselect_b32 s54, s6, s10
	v_add_u32_e32 v146, s12, v150
	s_cselect_b32 s41, s7, s23
	s_cselect_b32 s40, s8, s9
	s_add_i32 s13, 0, 0x14000
	ds_read_b128 v[138:141], v146
	ds_read_b128 v[142:145], v146 offset:1024
	ds_read_b128 v[154:157], v146 offset:2048
	ds_read_b128 v[158:161], v146 offset:3072
	v_add_u32_e32 v146, s13, v150
	ds_read_b128 v[162:165], v146
	ds_read_b128 v[166:169], v146 offset:1024
	ds_read_b128 v[170:173], v146 offset:2048
	ds_read_b128 v[174:177], v146 offset:3072
	s_add_u32 s10, s30, 0xfffc0000
	s_addc_u32 s11, s31, -1
	v_lshl_add_u64 v[190:191], s[10:11], 0, v[134:135]
	s_mov_b32 m0, s26
	s_nop 0
	global_load_lds_dwordx4 v[190:191], off
	v_lshl_add_u64 v[190:191], s[10:11], 0, v[136:137]
	s_mov_b32 m0, s67
	s_nop 0
	global_load_lds_dwordx4 v[190:191], off
	v_lshl_add_u64 v[190:191], s[30:31], 0, v[134:135]
	s_add_i32 m0, s63, 0xc000
	ds_read_b128 v[178:181], v152
	ds_read_b128 v[182:185], v152 offset:1024
	ds_read_b128 v[186:189], v152 offset:2048
	ds_read_b128 v[206:209], v152 offset:3072
	ds_read_b128 v[210:213], v152 offset:4096
	ds_read_b128 v[214:217], v152 offset:5120
	ds_read_b128 v[218:221], v152 offset:6144
	ds_read_b128 v[222:225], v152 offset:7168
	global_load_lds_dwordx4 v[190:191], off
	v_lshl_add_u64 v[190:191], s[30:31], 0, v[136:137]
	s_add_i32 m0, s63, 0xe000
	s_nop 0
	global_load_lds_dwordx4 v[190:191], off
	s_waitcnt vmcnt(8)
	s_waitcnt lgkmcnt(0)
	s_barrier
	s_setprio 1
	s_waitcnt lgkmcnt(0)
	v_mfma_f32_16x16x32_bf16 v[124:127], v[138:141], v[178:181], v[124:127]
	v_mfma_f32_16x16x32_bf16 v[120:123], v[154:157], v[178:181], v[120:123]
	v_mfma_f32_16x16x32_bf16 v[108:111], v[138:141], v[186:189], v[108:111]
	v_mfma_f32_16x16x32_bf16 v[104:107], v[154:157], v[186:189], v[104:107]
	v_mfma_f32_16x16x32_bf16 v[92:95], v[138:141], v[210:213], v[92:95]
	v_mfma_f32_16x16x32_bf16 v[88:91], v[154:157], v[210:213], v[88:91]
	v_mfma_f32_16x16x32_bf16 v[76:79], v[138:141], v[218:221], v[76:79]
	v_mfma_f32_16x16x32_bf16 v[72:75], v[154:157], v[218:221], v[72:75]
	v_mfma_f32_16x16x32_bf16 v[124:127], v[142:145], v[182:185], v[124:127]
	v_mfma_f32_16x16x32_bf16 v[120:123], v[158:161], v[182:185], v[120:123]
	v_mfma_f32_16x16x32_bf16 v[108:111], v[142:145], v[206:209], v[108:111]
	v_mfma_f32_16x16x32_bf16 v[104:107], v[158:161], v[206:209], v[104:107]
	v_mfma_f32_16x16x32_bf16 v[92:95], v[142:145], v[214:217], v[92:95]
	v_mfma_f32_16x16x32_bf16 v[88:91], v[158:161], v[214:217], v[88:91]
	v_mfma_f32_16x16x32_bf16 v[76:79], v[142:145], v[222:225], v[76:79]
	v_mfma_f32_16x16x32_bf16 v[72:75], v[158:161], v[222:225], v[72:75]
	s_setprio 0
	s_setprio 1
	v_mfma_f32_16x16x32_bf16 v[116:119], v[162:165], v[178:181], v[116:119]
	v_mfma_f32_16x16x32_bf16 v[112:115], v[170:173], v[178:181], v[112:115]
	v_mfma_f32_16x16x32_bf16 v[100:103], v[162:165], v[186:189], v[100:103]
	v_mfma_f32_16x16x32_bf16 v[96:99], v[170:173], v[186:189], v[96:99]
	v_mfma_f32_16x16x32_bf16 v[84:87], v[162:165], v[210:213], v[84:87]
	v_mfma_f32_16x16x32_bf16 v[80:83], v[170:173], v[210:213], v[80:83]
	v_mfma_f32_16x16x32_bf16 v[68:71], v[162:165], v[218:221], v[68:71]
	v_mfma_f32_16x16x32_bf16 v[64:67], v[170:173], v[218:221], v[64:67]
	v_mfma_f32_16x16x32_bf16 v[116:119], v[166:169], v[182:185], v[116:119]
	v_mfma_f32_16x16x32_bf16 v[112:115], v[174:177], v[182:185], v[112:115]
	v_mfma_f32_16x16x32_bf16 v[100:103], v[166:169], v[206:209], v[100:103]
	v_mfma_f32_16x16x32_bf16 v[96:99], v[174:177], v[206:209], v[96:99]
	v_mfma_f32_16x16x32_bf16 v[84:87], v[166:169], v[214:217], v[84:87]
	v_mfma_f32_16x16x32_bf16 v[80:83], v[174:177], v[214:217], v[80:83]
	v_mfma_f32_16x16x32_bf16 v[68:71], v[166:169], v[222:225], v[68:71]
	v_mfma_f32_16x16x32_bf16 v[64:67], v[174:177], v[222:225], v[64:67]
	s_setprio 0
	s_barrier
	s_add_i32 s10, s12, s62
	v_lshl_add_u64 v[190:191], s[40:41], 0, v[192:193]
	s_mov_b32 m0, s10
	ds_read_b128 v[178:181], v152 offset:16384
	ds_read_b128 v[182:185], v152 offset:17408
	ds_read_b128 v[186:189], v152 offset:18432
	ds_read_b128 v[206:209], v152 offset:19456
	ds_read_b128 v[210:213], v152 offset:20480
	ds_read_b128 v[214:217], v152 offset:21504
	ds_read_b128 v[218:221], v152 offset:22528
	ds_read_b128 v[222:225], v152 offset:23552
	global_load_lds_dwordx4 v[190:191], off
	s_add_i32 m0, s10, 0x2000
	s_add_u32 s10, s40, 0x40000
	v_lshl_add_u64 v[226:227], s[40:41], 0, v[132:133]
	s_addc_u32 s11, s41, 0
	s_add_i32 s12, s13, s62
	global_load_lds_dwordx4 v[226:227], off
	v_lshl_add_u64 v[228:229], s[10:11], 0, v[192:193]
	s_mov_b32 m0, s12
	v_lshl_add_u64 v[230:231], s[54:55], 0, v[130:131]
	global_load_lds_dwordx4 v[228:229], off
	v_lshl_add_u64 v[228:229], s[10:11], 0, v[132:133]
	s_add_i32 m0, s12, 0x2000
	s_nop 0
	global_load_lds_dwordx4 v[228:229], off
	v_lshl_add_u64 v[228:229], s[54:55], 0, v[128:129]
	s_waitcnt vmcnt(6)
	s_waitcnt lgkmcnt(0)
	s_barrier
	s_setprio 1
	s_waitcnt lgkmcnt(0)
	v_mfma_f32_16x16x32_bf16 v[60:63], v[138:141], v[178:181], v[60:63]
	v_mfma_f32_16x16x32_bf16 v[56:59], v[154:157], v[178:181], v[56:59]
	v_mfma_f32_16x16x32_bf16 v[44:47], v[138:141], v[186:189], v[44:47]
	v_mfma_f32_16x16x32_bf16 v[40:43], v[154:157], v[186:189], v[40:43]
	v_mfma_f32_16x16x32_bf16 v[28:31], v[138:141], v[210:213], v[28:31]
	v_mfma_f32_16x16x32_bf16 v[24:27], v[154:157], v[210:213], v[24:27]
	v_mfma_f32_16x16x32_bf16 v[12:15], v[138:141], v[218:221], v[12:15]
	v_mfma_f32_16x16x32_bf16 v[8:11], v[154:157], v[218:221], v[8:11]
	v_mfma_f32_16x16x32_bf16 v[60:63], v[142:145], v[182:185], v[60:63]
	v_mfma_f32_16x16x32_bf16 v[56:59], v[158:161], v[182:185], v[56:59]
	v_mfma_f32_16x16x32_bf16 v[44:47], v[142:145], v[206:209], v[44:47]
	v_mfma_f32_16x16x32_bf16 v[40:43], v[158:161], v[206:209], v[40:43]
	v_mfma_f32_16x16x32_bf16 v[28:31], v[142:145], v[214:217], v[28:31]
	v_mfma_f32_16x16x32_bf16 v[24:27], v[158:161], v[214:217], v[24:27]
	v_mfma_f32_16x16x32_bf16 v[12:15], v[142:145], v[222:225], v[12:15]
	v_mfma_f32_16x16x32_bf16 v[8:11], v[158:161], v[222:225], v[8:11]
	s_setprio 0
	s_setprio 1
	v_mfma_f32_16x16x32_bf16 v[52:55], v[162:165], v[178:181], v[52:55]
	v_mfma_f32_16x16x32_bf16 v[48:51], v[170:173], v[178:181], v[48:51]
	v_mfma_f32_16x16x32_bf16 v[36:39], v[162:165], v[186:189], v[36:39]
	v_mfma_f32_16x16x32_bf16 v[32:35], v[170:173], v[186:189], v[32:35]
	v_mfma_f32_16x16x32_bf16 v[20:23], v[162:165], v[210:213], v[20:23]
	v_mfma_f32_16x16x32_bf16 v[16:19], v[170:173], v[210:213], v[16:19]
	v_mfma_f32_16x16x32_bf16 v[4:7], v[162:165], v[218:221], v[4:7]
	v_mfma_f32_16x16x32_bf16 v[0:3], v[170:173], v[218:221], v[0:3]
	v_mfma_f32_16x16x32_bf16 v[52:55], v[166:169], v[182:185], v[52:55]
	v_mfma_f32_16x16x32_bf16 v[48:51], v[174:177], v[182:185], v[48:51]
	v_mfma_f32_16x16x32_bf16 v[36:39], v[166:169], v[206:209], v[36:39]
	v_mfma_f32_16x16x32_bf16 v[32:35], v[174:177], v[206:209], v[32:35]
	v_mfma_f32_16x16x32_bf16 v[20:23], v[166:169], v[214:217], v[20:23]
	v_mfma_f32_16x16x32_bf16 v[16:19], v[174:177], v[214:217], v[16:19]
	v_mfma_f32_16x16x32_bf16 v[4:7], v[166:169], v[222:225], v[4:7]
	v_mfma_f32_16x16x32_bf16 v[0:3], v[174:177], v[222:225], v[0:3]
	s_setprio 0
	s_barrier
	s_add_i32 s12, 0, 0x18000
	v_add_u32_e32 v146, s12, v150
	s_add_i32 s13, 0, 0x1c000
	ds_read_b128 v[138:141], v146
	ds_read_b128 v[142:145], v146 offset:1024
	ds_read_b128 v[154:157], v146 offset:2048
	ds_read_b128 v[158:161], v146 offset:3072
	v_add_u32_e32 v146, s13, v150
	ds_read_b128 v[162:165], v146
	ds_read_b128 v[166:169], v146 offset:1024
	ds_read_b128 v[170:173], v146 offset:2048
	ds_read_b128 v[174:177], v146 offset:3072
	s_mov_b32 m0, s63
	s_nop 0
	global_load_lds_dwordx4 v[228:229], off
	s_mov_b32 m0, s64
	s_nop 0
	global_load_lds_dwordx4 v[230:231], off
	s_add_u32 s10, s54, 0x40000
	s_addc_u32 s11, s55, 0
	s_mov_b32 m0, s65
	v_lshl_add_u64 v[232:233], s[10:11], 0, v[128:129]
	ds_read_b128 v[178:181], v152 offset:32768
	ds_read_b128 v[182:185], v152 offset:33792
	ds_read_b128 v[186:189], v152 offset:34816
	ds_read_b128 v[206:209], v152 offset:35840
	ds_read_b128 v[210:213], v152 offset:36864
	ds_read_b128 v[214:217], v152 offset:37888
	ds_read_b128 v[218:221], v152 offset:38912
	ds_read_b128 v[222:225], v152 offset:39936
	global_load_lds_dwordx4 v[232:233], off
	v_lshl_add_u64 v[232:233], s[10:11], 0, v[130:131]
	s_mov_b32 m0, s66
	s_nop 0
	global_load_lds_dwordx4 v[232:233], off
	s_waitcnt vmcnt(8)
	s_waitcnt lgkmcnt(0)
	s_barrier
	s_setprio 1
	s_waitcnt lgkmcnt(0)
	v_mfma_f32_16x16x32_bf16 v[124:127], v[138:141], v[178:181], v[124:127]
	v_mfma_f32_16x16x32_bf16 v[120:123], v[154:157], v[178:181], v[120:123]
	v_mfma_f32_16x16x32_bf16 v[108:111], v[138:141], v[186:189], v[108:111]
	v_mfma_f32_16x16x32_bf16 v[104:107], v[154:157], v[186:189], v[104:107]
	v_mfma_f32_16x16x32_bf16 v[92:95], v[138:141], v[210:213], v[92:95]
	v_mfma_f32_16x16x32_bf16 v[88:91], v[154:157], v[210:213], v[88:91]
	v_mfma_f32_16x16x32_bf16 v[76:79], v[138:141], v[218:221], v[76:79]
	v_mfma_f32_16x16x32_bf16 v[72:75], v[154:157], v[218:221], v[72:75]
	v_mfma_f32_16x16x32_bf16 v[124:127], v[142:145], v[182:185], v[124:127]
	v_mfma_f32_16x16x32_bf16 v[120:123], v[158:161], v[182:185], v[120:123]
	v_mfma_f32_16x16x32_bf16 v[108:111], v[142:145], v[206:209], v[108:111]
	v_mfma_f32_16x16x32_bf16 v[104:107], v[158:161], v[206:209], v[104:107]
	v_mfma_f32_16x16x32_bf16 v[92:95], v[142:145], v[214:217], v[92:95]
	v_mfma_f32_16x16x32_bf16 v[88:91], v[158:161], v[214:217], v[88:91]
	v_mfma_f32_16x16x32_bf16 v[76:79], v[142:145], v[222:225], v[76:79]
	v_mfma_f32_16x16x32_bf16 v[72:75], v[158:161], v[222:225], v[72:75]
	s_setprio 0
	s_setprio 1
	v_mfma_f32_16x16x32_bf16 v[116:119], v[162:165], v[178:181], v[116:119]
	v_mfma_f32_16x16x32_bf16 v[112:115], v[170:173], v[178:181], v[112:115]
	v_mfma_f32_16x16x32_bf16 v[100:103], v[162:165], v[186:189], v[100:103]
	v_mfma_f32_16x16x32_bf16 v[96:99], v[170:173], v[186:189], v[96:99]
	v_mfma_f32_16x16x32_bf16 v[84:87], v[162:165], v[210:213], v[84:87]
	v_mfma_f32_16x16x32_bf16 v[80:83], v[170:173], v[210:213], v[80:83]
	v_mfma_f32_16x16x32_bf16 v[68:71], v[162:165], v[218:221], v[68:71]
	v_mfma_f32_16x16x32_bf16 v[64:67], v[170:173], v[218:221], v[64:67]
	v_mfma_f32_16x16x32_bf16 v[116:119], v[166:169], v[182:185], v[116:119]
	v_mfma_f32_16x16x32_bf16 v[112:115], v[174:177], v[182:185], v[112:115]
	v_mfma_f32_16x16x32_bf16 v[100:103], v[166:169], v[206:209], v[100:103]
	v_mfma_f32_16x16x32_bf16 v[96:99], v[174:177], v[206:209], v[96:99]
	v_mfma_f32_16x16x32_bf16 v[84:87], v[166:169], v[214:217], v[84:87]
	v_mfma_f32_16x16x32_bf16 v[80:83], v[174:177], v[214:217], v[80:83]
	v_mfma_f32_16x16x32_bf16 v[68:71], v[166:169], v[222:225], v[68:71]
	v_mfma_f32_16x16x32_bf16 v[64:67], v[174:177], v[222:225], v[64:67]
	s_setprio 0
	s_barrier
	s_add_i32 s10, s12, s62
	v_lshl_add_u64 v[190:191], v[190:191], 0, s[28:29]
	s_mov_b32 m0, s10
	ds_read_b128 v[178:181], v152 offset:49152
	ds_read_b128 v[182:185], v152 offset:50176
	ds_read_b128 v[186:189], v152 offset:51200
	ds_read_b128 v[206:209], v152 offset:52224
	ds_read_b128 v[210:213], v152 offset:53248
	ds_read_b128 v[214:217], v152 offset:54272
	ds_read_b128 v[218:221], v152 offset:55296
	ds_read_b128 v[222:225], v152 offset:56320
	global_load_lds_dwordx4 v[190:191], off
	s_add_i32 m0, s10, 0x2000
	s_add_u32 s10, s40, 0x40080
	v_lshl_add_u64 v[190:191], v[226:227], 0, s[28:29]
	s_addc_u32 s11, s41, 0
	s_add_i32 s12, s13, s62
	global_load_lds_dwordx4 v[190:191], off
	v_lshl_add_u64 v[190:191], s[10:11], 0, v[192:193]
	s_mov_b32 m0, s12
	s_nop 0
	global_load_lds_dwordx4 v[190:191], off
	v_lshl_add_u64 v[190:191], s[10:11], 0, v[132:133]
	s_add_i32 m0, s12, 0x2000
	s_nop 0
	global_load_lds_dwordx4 v[190:191], off
	s_waitcnt vmcnt(6)
	s_waitcnt lgkmcnt(0)
	s_barrier
	s_setprio 1
	s_waitcnt lgkmcnt(0)
	v_mfma_f32_16x16x32_bf16 v[60:63], v[138:141], v[178:181], v[60:63]
	v_mfma_f32_16x16x32_bf16 v[56:59], v[154:157], v[178:181], v[56:59]
	v_mfma_f32_16x16x32_bf16 v[44:47], v[138:141], v[186:189], v[44:47]
	v_mfma_f32_16x16x32_bf16 v[40:43], v[154:157], v[186:189], v[40:43]
	v_mfma_f32_16x16x32_bf16 v[28:31], v[138:141], v[210:213], v[28:31]
	v_mfma_f32_16x16x32_bf16 v[24:27], v[154:157], v[210:213], v[24:27]
	v_mfma_f32_16x16x32_bf16 v[12:15], v[138:141], v[218:221], v[12:15]
	v_mfma_f32_16x16x32_bf16 v[8:11], v[154:157], v[218:221], v[8:11]
	v_mfma_f32_16x16x32_bf16 v[60:63], v[142:145], v[182:185], v[60:63]
	v_mfma_f32_16x16x32_bf16 v[56:59], v[158:161], v[182:185], v[56:59]
	v_mfma_f32_16x16x32_bf16 v[44:47], v[142:145], v[206:209], v[44:47]
	v_mfma_f32_16x16x32_bf16 v[40:43], v[158:161], v[206:209], v[40:43]
	v_mfma_f32_16x16x32_bf16 v[28:31], v[142:145], v[214:217], v[28:31]
	v_mfma_f32_16x16x32_bf16 v[24:27], v[158:161], v[214:217], v[24:27]
	v_mfma_f32_16x16x32_bf16 v[12:15], v[142:145], v[222:225], v[12:15]
	v_mfma_f32_16x16x32_bf16 v[8:11], v[158:161], v[222:225], v[8:11]
	s_setprio 0
	s_setprio 1
	v_mfma_f32_16x16x32_bf16 v[52:55], v[162:165], v[178:181], v[52:55]
	v_mfma_f32_16x16x32_bf16 v[48:51], v[170:173], v[178:181], v[48:51]
	v_mfma_f32_16x16x32_bf16 v[36:39], v[162:165], v[186:189], v[36:39]
	v_mfma_f32_16x16x32_bf16 v[32:35], v[170:173], v[186:189], v[32:35]
	v_mfma_f32_16x16x32_bf16 v[20:23], v[162:165], v[210:213], v[20:23]
	v_mfma_f32_16x16x32_bf16 v[16:19], v[170:173], v[210:213], v[16:19]
	v_mfma_f32_16x16x32_bf16 v[4:7], v[162:165], v[218:221], v[4:7]
	v_mfma_f32_16x16x32_bf16 v[0:3], v[170:173], v[218:221], v[0:3]
	v_mfma_f32_16x16x32_bf16 v[52:55], v[166:169], v[182:185], v[52:55]
	v_mfma_f32_16x16x32_bf16 v[48:51], v[174:177], v[182:185], v[48:51]
	v_mfma_f32_16x16x32_bf16 v[36:39], v[166:169], v[206:209], v[36:39]
	v_mfma_f32_16x16x32_bf16 v[32:35], v[174:177], v[206:209], v[32:35]
	v_mfma_f32_16x16x32_bf16 v[20:23], v[166:169], v[214:217], v[20:23]
	v_mfma_f32_16x16x32_bf16 v[16:19], v[174:177], v[214:217], v[16:19]
	v_mfma_f32_16x16x32_bf16 v[4:7], v[166:169], v[222:225], v[4:7]
	v_mfma_f32_16x16x32_bf16 v[0:3], v[174:177], v[222:225], v[0:3]
	s_setprio 0
	s_barrier
	s_add_i32 s47, s47, 2
	s_add_u32 s30, s30, 0x100
	s_addc_u32 s31, s31, 0
	s_add_u32 s9, s9, 0x100
	s_addc_u32 s23, s23, 0
	s_cmp_gt_u32 s47, 13
	s_cbranch_scc0 .LBB0_1144
	s_and_b64 vcc, exec, s[44:45]
	s_cbranch_vccz .LBB0_1147
	s_barrier

.LBB0_1229:
	s_add_u32 s10, s56, 0xfff00080
	s_addc_u32 s11, s57, -1
	s_add_i32 s12, 0, 0x10000
	s_cmp_eq_u32 s83, 60
	s_cselect_b32 s61, s47, s11
	s_cselect_b32 s60, s53, s10
	s_cselect_b32 s59, s45, s82
	s_cselect_b32 s58, s78, s79
	s_add_i32 s13, 0, 0x14000
	v_add_u32_e32 v156, s12, v145
	v_add_u32_e32 v172, s13, v145
	ds_read_b128 v[138:141], v156
	ds_read_b128 v[148:151], v156 offset:1024
	ds_read_b128 v[152:155], v156 offset:2048
	ds_read_b128 v[156:159], v156 offset:3072
	ds_read_b128 v[160:163], v172
	ds_read_b128 v[164:167], v172 offset:1024
	ds_read_b128 v[168:171], v172 offset:2048
	ds_read_b128 v[172:175], v172 offset:3072
	s_add_u32 s10, s56, 0xfff00000
	s_addc_u32 s11, s57, -1
	v_lshl_add_u64 v[222:223], s[10:11], 0, v[134:135]
	s_mov_b32 m0, s64
	s_nop 0
	global_load_lds_dwordx4 v[222:223], off
	v_lshl_add_u64 v[222:223], s[10:11], 0, v[136:137]
	s_mov_b32 m0, s65
	s_nop 0
	global_load_lds_dwordx4 v[222:223], off
	v_lshl_add_u64 v[222:223], s[56:57], 0, v[134:135]
	s_add_i32 m0, s9, 0xc000
	ds_read_b128 v[176:179], v147
	ds_read_b128 v[180:183], v147 offset:1024
	ds_read_b128 v[184:187], v147 offset:2048
	ds_read_b128 v[188:191], v147 offset:3072
	ds_read_b128 v[206:209], v147 offset:4096
	ds_read_b128 v[210:213], v147 offset:5120
	ds_read_b128 v[214:217], v147 offset:6144
	ds_read_b128 v[218:221], v147 offset:7168
	global_load_lds_dwordx4 v[222:223], off
	v_lshl_add_u64 v[222:223], s[56:57], 0, v[136:137]
	s_add_i32 m0, s9, 0xe000
	s_nop 0
	global_load_lds_dwordx4 v[222:223], off
	s_waitcnt vmcnt(8)
	s_waitcnt lgkmcnt(0)
	s_barrier
	s_setprio 1
	s_waitcnt lgkmcnt(0)
	v_mfma_f32_16x16x32_bf16 v[124:127], v[138:141], v[176:179], v[124:127]
	v_mfma_f32_16x16x32_bf16 v[120:123], v[152:155], v[176:179], v[120:123]
	v_mfma_f32_16x16x32_bf16 v[108:111], v[138:141], v[184:187], v[108:111]
	v_mfma_f32_16x16x32_bf16 v[104:107], v[152:155], v[184:187], v[104:107]
	v_mfma_f32_16x16x32_bf16 v[92:95], v[138:141], v[206:209], v[92:95]
	v_mfma_f32_16x16x32_bf16 v[88:91], v[152:155], v[206:209], v[88:91]
	v_mfma_f32_16x16x32_bf16 v[76:79], v[138:141], v[214:217], v[76:79]
	v_mfma_f32_16x16x32_bf16 v[72:75], v[152:155], v[214:217], v[72:75]
	v_mfma_f32_16x16x32_bf16 v[124:127], v[148:151], v[180:183], v[124:127]
	v_mfma_f32_16x16x32_bf16 v[120:123], v[156:159], v[180:183], v[120:123]
	v_mfma_f32_16x16x32_bf16 v[108:111], v[148:151], v[188:191], v[108:111]
	v_mfma_f32_16x16x32_bf16 v[104:107], v[156:159], v[188:191], v[104:107]
	v_mfma_f32_16x16x32_bf16 v[92:95], v[148:151], v[210:213], v[92:95]
	v_mfma_f32_16x16x32_bf16 v[88:91], v[156:159], v[210:213], v[88:91]
	v_mfma_f32_16x16x32_bf16 v[76:79], v[148:151], v[218:221], v[76:79]
	v_mfma_f32_16x16x32_bf16 v[72:75], v[156:159], v[218:221], v[72:75]
	s_setprio 0
	s_setprio 1
	v_mfma_f32_16x16x32_bf16 v[116:119], v[160:163], v[176:179], v[116:119]
	v_mfma_f32_16x16x32_bf16 v[112:115], v[168:171], v[176:179], v[112:115]
	v_mfma_f32_16x16x32_bf16 v[100:103], v[160:163], v[184:187], v[100:103]
	v_mfma_f32_16x16x32_bf16 v[96:99], v[168:171], v[184:187], v[96:99]
	v_mfma_f32_16x16x32_bf16 v[84:87], v[160:163], v[206:209], v[84:87]
	v_mfma_f32_16x16x32_bf16 v[80:83], v[168:171], v[206:209], v[80:83]
	v_mfma_f32_16x16x32_bf16 v[68:71], v[160:163], v[214:217], v[68:71]
	v_mfma_f32_16x16x32_bf16 v[64:67], v[168:171], v[214:217], v[64:67]
	v_mfma_f32_16x16x32_bf16 v[116:119], v[164:167], v[180:183], v[116:119]
	v_mfma_f32_16x16x32_bf16 v[112:115], v[172:175], v[180:183], v[112:115]
	v_mfma_f32_16x16x32_bf16 v[100:103], v[164:167], v[188:191], v[100:103]
	v_mfma_f32_16x16x32_bf16 v[96:99], v[172:175], v[188:191], v[96:99]
	v_mfma_f32_16x16x32_bf16 v[84:87], v[164:167], v[210:213], v[84:87]
	v_mfma_f32_16x16x32_bf16 v[80:83], v[172:175], v[210:213], v[80:83]
	v_mfma_f32_16x16x32_bf16 v[68:71], v[164:167], v[218:221], v[68:71]
	v_mfma_f32_16x16x32_bf16 v[64:67], v[172:175], v[218:221], v[64:67]
	s_setprio 0
	s_barrier
	s_add_i32 s10, s12, s8
	v_lshl_add_u64 v[222:223], s[58:59], 0, v[192:193]
	s_mov_b32 m0, s10
	ds_read_b128 v[176:179], v147 offset:16384
	ds_read_b128 v[180:183], v147 offset:17408
	ds_read_b128 v[184:187], v147 offset:18432
	ds_read_b128 v[188:191], v147 offset:19456
	ds_read_b128 v[206:209], v147 offset:20480
	ds_read_b128 v[210:213], v147 offset:21504
	ds_read_b128 v[214:217], v147 offset:22528
	ds_read_b128 v[218:221], v147 offset:23552
	global_load_lds_dwordx4 v[222:223], off
	s_add_i32 m0, s10, 0x2000
	s_add_u32 s10, s58, 0x100000
	v_lshl_add_u64 v[224:225], s[58:59], 0, v[132:133]
	s_addc_u32 s11, s59, 0
	s_add_i32 s12, s13, s8
	global_load_lds_dwordx4 v[224:225], off
	v_lshl_add_u64 v[226:227], s[10:11], 0, v[192:193]
	s_mov_b32 m0, s12
	v_lshl_add_u64 v[228:229], s[60:61], 0, v[130:131]
	global_load_lds_dwordx4 v[226:227], off
	v_lshl_add_u64 v[226:227], s[10:11], 0, v[132:133]
	s_add_i32 m0, s12, 0x2000
	s_nop 0
	global_load_lds_dwordx4 v[226:227], off
	v_lshl_add_u64 v[226:227], s[60:61], 0, v[128:129]
	s_waitcnt vmcnt(6)
	s_waitcnt lgkmcnt(0)
	s_barrier
	s_setprio 1
	s_waitcnt lgkmcnt(0)
	v_mfma_f32_16x16x32_bf16 v[60:63], v[138:141], v[176:179], v[60:63]
	v_mfma_f32_16x16x32_bf16 v[56:59], v[152:155], v[176:179], v[56:59]
	v_mfma_f32_16x16x32_bf16 v[44:47], v[138:141], v[184:187], v[44:47]
	v_mfma_f32_16x16x32_bf16 v[40:43], v[152:155], v[184:187], v[40:43]
	v_mfma_f32_16x16x32_bf16 v[28:31], v[138:141], v[206:209], v[28:31]
	v_mfma_f32_16x16x32_bf16 v[24:27], v[152:155], v[206:209], v[24:27]
	v_mfma_f32_16x16x32_bf16 v[12:15], v[138:141], v[214:217], v[12:15]
	v_mfma_f32_16x16x32_bf16 v[8:11], v[152:155], v[214:217], v[8:11]
	v_mfma_f32_16x16x32_bf16 v[60:63], v[148:151], v[180:183], v[60:63]
	v_mfma_f32_16x16x32_bf16 v[56:59], v[156:159], v[180:183], v[56:59]
	v_mfma_f32_16x16x32_bf16 v[44:47], v[148:151], v[188:191], v[44:47]
	v_mfma_f32_16x16x32_bf16 v[40:43], v[156:159], v[188:191], v[40:43]
	v_mfma_f32_16x16x32_bf16 v[28:31], v[148:151], v[210:213], v[28:31]
	v_mfma_f32_16x16x32_bf16 v[24:27], v[156:159], v[210:213], v[24:27]
	v_mfma_f32_16x16x32_bf16 v[12:15], v[148:151], v[218:221], v[12:15]
	v_mfma_f32_16x16x32_bf16 v[8:11], v[156:159], v[218:221], v[8:11]
	s_setprio 0
	s_setprio 1
	v_mfma_f32_16x16x32_bf16 v[52:55], v[160:163], v[176:179], v[52:55]
	v_mfma_f32_16x16x32_bf16 v[48:51], v[168:171], v[176:179], v[48:51]
	v_mfma_f32_16x16x32_bf16 v[36:39], v[160:163], v[184:187], v[36:39]
	v_mfma_f32_16x16x32_bf16 v[32:35], v[168:171], v[184:187], v[32:35]
	v_mfma_f32_16x16x32_bf16 v[20:23], v[160:163], v[206:209], v[20:23]
	v_mfma_f32_16x16x32_bf16 v[16:19], v[168:171], v[206:209], v[16:19]
	v_mfma_f32_16x16x32_bf16 v[4:7], v[160:163], v[214:217], v[4:7]
	v_mfma_f32_16x16x32_bf16 v[0:3], v[168:171], v[214:217], v[0:3]
	v_mfma_f32_16x16x32_bf16 v[52:55], v[164:167], v[180:183], v[52:55]
	v_mfma_f32_16x16x32_bf16 v[48:51], v[172:175], v[180:183], v[48:51]
	v_mfma_f32_16x16x32_bf16 v[36:39], v[164:167], v[188:191], v[36:39]
	v_mfma_f32_16x16x32_bf16 v[32:35], v[172:175], v[188:191], v[32:35]
	v_mfma_f32_16x16x32_bf16 v[20:23], v[164:167], v[210:213], v[20:23]
	v_mfma_f32_16x16x32_bf16 v[16:19], v[172:175], v[210:213], v[16:19]
	v_mfma_f32_16x16x32_bf16 v[4:7], v[164:167], v[218:221], v[4:7]
	v_mfma_f32_16x16x32_bf16 v[0:3], v[172:175], v[218:221], v[0:3]
	s_setprio 0
	s_barrier
	s_add_i32 s12, 0, 0x18000
	s_add_i32 s13, 0, 0x1c000
	v_add_u32_e32 v156, s12, v145
	v_add_u32_e32 v172, s13, v145
	ds_read_b128 v[138:141], v156
	ds_read_b128 v[148:151], v156 offset:1024
	ds_read_b128 v[152:155], v156 offset:2048
	ds_read_b128 v[156:159], v156 offset:3072
	ds_read_b128 v[160:163], v172
	ds_read_b128 v[164:167], v172 offset:1024
	ds_read_b128 v[168:171], v172 offset:2048
	ds_read_b128 v[172:175], v172 offset:3072
	s_mov_b32 m0, s9
	s_nop 0
	global_load_lds_dwordx4 v[226:227], off
	s_mov_b32 m0, s55
	s_nop 0
	global_load_lds_dwordx4 v[228:229], off
	s_add_u32 s10, s60, 0x100000
	s_addc_u32 s11, s61, 0
	s_mov_b32 m0, s62
	v_lshl_add_u64 v[230:231], s[10:11], 0, v[128:129]
	ds_read_b128 v[176:179], v147 offset:32768
	ds_read_b128 v[180:183], v147 offset:33792
	ds_read_b128 v[184:187], v147 offset:34816
	ds_read_b128 v[188:191], v147 offset:35840
	ds_read_b128 v[206:209], v147 offset:36864
	ds_read_b128 v[210:213], v147 offset:37888
	ds_read_b128 v[214:217], v147 offset:38912
	ds_read_b128 v[218:221], v147 offset:39936
	global_load_lds_dwordx4 v[230:231], off
	v_lshl_add_u64 v[230:231], s[10:11], 0, v[130:131]
	s_mov_b32 m0, s63
	s_nop 0
	global_load_lds_dwordx4 v[230:231], off
	s_waitcnt vmcnt(8)
	s_waitcnt lgkmcnt(0)
	s_barrier
	s_setprio 1
	s_waitcnt lgkmcnt(0)
	v_mfma_f32_16x16x32_bf16 v[124:127], v[138:141], v[176:179], v[124:127]
	v_mfma_f32_16x16x32_bf16 v[120:123], v[152:155], v[176:179], v[120:123]
	v_mfma_f32_16x16x32_bf16 v[108:111], v[138:141], v[184:187], v[108:111]
	v_mfma_f32_16x16x32_bf16 v[104:107], v[152:155], v[184:187], v[104:107]
	v_mfma_f32_16x16x32_bf16 v[92:95], v[138:141], v[206:209], v[92:95]
	v_mfma_f32_16x16x32_bf16 v[88:91], v[152:155], v[206:209], v[88:91]
	v_mfma_f32_16x16x32_bf16 v[76:79], v[138:141], v[214:217], v[76:79]
	v_mfma_f32_16x16x32_bf16 v[72:75], v[152:155], v[214:217], v[72:75]
	v_mfma_f32_16x16x32_bf16 v[124:127], v[148:151], v[180:183], v[124:127]
	v_mfma_f32_16x16x32_bf16 v[120:123], v[156:159], v[180:183], v[120:123]
	v_mfma_f32_16x16x32_bf16 v[108:111], v[148:151], v[188:191], v[108:111]
	v_mfma_f32_16x16x32_bf16 v[104:107], v[156:159], v[188:191], v[104:107]
	v_mfma_f32_16x16x32_bf16 v[92:95], v[148:151], v[210:213], v[92:95]
	v_mfma_f32_16x16x32_bf16 v[88:91], v[156:159], v[210:213], v[88:91]
	v_mfma_f32_16x16x32_bf16 v[76:79], v[148:151], v[218:221], v[76:79]
	v_mfma_f32_16x16x32_bf16 v[72:75], v[156:159], v[218:221], v[72:75]
	s_setprio 0
	s_setprio 1
	v_mfma_f32_16x16x32_bf16 v[116:119], v[160:163], v[176:179], v[116:119]
	v_mfma_f32_16x16x32_bf16 v[112:115], v[168:171], v[176:179], v[112:115]
	v_mfma_f32_16x16x32_bf16 v[100:103], v[160:163], v[184:187], v[100:103]
	v_mfma_f32_16x16x32_bf16 v[96:99], v[168:171], v[184:187], v[96:99]
	v_mfma_f32_16x16x32_bf16 v[84:87], v[160:163], v[206:209], v[84:87]
	v_mfma_f32_16x16x32_bf16 v[80:83], v[168:171], v[206:209], v[80:83]
	v_mfma_f32_16x16x32_bf16 v[68:71], v[160:163], v[214:217], v[68:71]
	v_mfma_f32_16x16x32_bf16 v[64:67], v[168:171], v[214:217], v[64:67]
	v_mfma_f32_16x16x32_bf16 v[116:119], v[164:167], v[180:183], v[116:119]
	v_mfma_f32_16x16x32_bf16 v[112:115], v[172:175], v[180:183], v[112:115]
	v_mfma_f32_16x16x32_bf16 v[100:103], v[164:167], v[188:191], v[100:103]
	v_mfma_f32_16x16x32_bf16 v[96:99], v[172:175], v[188:191], v[96:99]
	v_mfma_f32_16x16x32_bf16 v[84:87], v[164:167], v[210:213], v[84:87]
	v_mfma_f32_16x16x32_bf16 v[80:83], v[172:175], v[210:213], v[80:83]
	v_mfma_f32_16x16x32_bf16 v[68:71], v[164:167], v[218:221], v[68:71]
	v_mfma_f32_16x16x32_bf16 v[64:67], v[172:175], v[218:221], v[64:67]
	s_setprio 0
	s_barrier
	s_add_i32 s10, s12, s8
	v_lshl_add_u64 v[222:223], v[222:223], 0, s[28:29]
	s_mov_b32 m0, s10
	ds_read_b128 v[176:179], v147 offset:49152
	ds_read_b128 v[180:183], v147 offset:50176
	ds_read_b128 v[184:187], v147 offset:51200
	ds_read_b128 v[188:191], v147 offset:52224
	ds_read_b128 v[206:209], v147 offset:53248
	ds_read_b128 v[210:213], v147 offset:54272
	ds_read_b128 v[214:217], v147 offset:55296
	ds_read_b128 v[218:221], v147 offset:56320
	global_load_lds_dwordx4 v[222:223], off
	s_add_i32 m0, s10, 0x2000
	s_add_u32 s10, s58, 0x100080
	v_lshl_add_u64 v[222:223], v[224:225], 0, s[28:29]
	s_addc_u32 s11, s59, 0
	s_add_i32 s12, s13, s8
	global_load_lds_dwordx4 v[222:223], off
	v_lshl_add_u64 v[222:223], s[10:11], 0, v[192:193]
	s_mov_b32 m0, s12
	s_nop 0
	global_load_lds_dwordx4 v[222:223], off
	v_lshl_add_u64 v[222:223], s[10:11], 0, v[132:133]
	s_add_i32 m0, s12, 0x2000
	s_nop 0
	global_load_lds_dwordx4 v[222:223], off
	s_waitcnt vmcnt(6)
	s_waitcnt lgkmcnt(0)
	s_barrier
	s_setprio 1
	s_waitcnt lgkmcnt(0)
	v_mfma_f32_16x16x32_bf16 v[60:63], v[138:141], v[176:179], v[60:63]
	v_mfma_f32_16x16x32_bf16 v[56:59], v[152:155], v[176:179], v[56:59]
	v_mfma_f32_16x16x32_bf16 v[44:47], v[138:141], v[184:187], v[44:47]
	v_mfma_f32_16x16x32_bf16 v[40:43], v[152:155], v[184:187], v[40:43]
	v_mfma_f32_16x16x32_bf16 v[28:31], v[138:141], v[206:209], v[28:31]
	v_mfma_f32_16x16x32_bf16 v[24:27], v[152:155], v[206:209], v[24:27]
	v_mfma_f32_16x16x32_bf16 v[12:15], v[138:141], v[214:217], v[12:15]
	v_mfma_f32_16x16x32_bf16 v[8:11], v[152:155], v[214:217], v[8:11]
	v_mfma_f32_16x16x32_bf16 v[60:63], v[148:151], v[180:183], v[60:63]
	v_mfma_f32_16x16x32_bf16 v[56:59], v[156:159], v[180:183], v[56:59]
	v_mfma_f32_16x16x32_bf16 v[44:47], v[148:151], v[188:191], v[44:47]
	v_mfma_f32_16x16x32_bf16 v[40:43], v[156:159], v[188:191], v[40:43]
	v_mfma_f32_16x16x32_bf16 v[28:31], v[148:151], v[210:213], v[28:31]
	v_mfma_f32_16x16x32_bf16 v[24:27], v[156:159], v[210:213], v[24:27]
	v_mfma_f32_16x16x32_bf16 v[12:15], v[148:151], v[218:221], v[12:15]
	v_mfma_f32_16x16x32_bf16 v[8:11], v[156:159], v[218:221], v[8:11]
	s_setprio 0
	s_setprio 1
	v_mfma_f32_16x16x32_bf16 v[52:55], v[160:163], v[176:179], v[52:55]
	v_mfma_f32_16x16x32_bf16 v[48:51], v[168:171], v[176:179], v[48:51]
	v_mfma_f32_16x16x32_bf16 v[36:39], v[160:163], v[184:187], v[36:39]
	v_mfma_f32_16x16x32_bf16 v[32:35], v[168:171], v[184:187], v[32:35]
	v_mfma_f32_16x16x32_bf16 v[20:23], v[160:163], v[206:209], v[20:23]
	v_mfma_f32_16x16x32_bf16 v[16:19], v[168:171], v[206:209], v[16:19]
	v_mfma_f32_16x16x32_bf16 v[4:7], v[160:163], v[214:217], v[4:7]
	v_mfma_f32_16x16x32_bf16 v[0:3], v[168:171], v[214:217], v[0:3]
	v_mfma_f32_16x16x32_bf16 v[52:55], v[164:167], v[180:183], v[52:55]
	v_mfma_f32_16x16x32_bf16 v[48:51], v[172:175], v[180:183], v[48:51]
	v_mfma_f32_16x16x32_bf16 v[36:39], v[164:167], v[188:191], v[36:39]
	v_mfma_f32_16x16x32_bf16 v[32:35], v[172:175], v[188:191], v[32:35]
	v_mfma_f32_16x16x32_bf16 v[20:23], v[164:167], v[210:213], v[20:23]
	v_mfma_f32_16x16x32_bf16 v[16:19], v[172:175], v[210:213], v[16:19]
	v_mfma_f32_16x16x32_bf16 v[4:7], v[164:167], v[218:221], v[4:7]
	v_mfma_f32_16x16x32_bf16 v[0:3], v[172:175], v[218:221], v[0:3]
	s_setprio 0
	s_barrier
	s_add_i32 s83, s83, 2
	s_add_u32 s56, s56, 0x100
	s_addc_u32 s57, s57, 0
	s_add_u32 s79, s79, 0x100
	s_addc_u32 s82, s82, 0
	s_cmp_gt_u32 s83, 61
	s_cbranch_scc0 .LBB0_1229
	s_and_b64 vcc, exec, s[42:43]
	s_cbranch_vccz .LBB0_1232
	s_barrier
